# loop-edge: redundant post-barrier lgkmcnt(0) removed from the head of every MFMA segment in the three GEMM K-loops (the pre-barrier lgkmcnt(0) already covers it), on top of v23
# baseline (speedup 1.0000x reference)
; #define PG8_STAGE(bufoff, gbase, voff) do { _Pragma("unroll") for (int _i = 0; _i < 2; ++_i) \
;         __builtin_amdgcn_global_load_lds((const unsigned*)((const char*)(gbase) + (voff)[_i]), (LAS unsigned*)(lds + (bufoff) + ldsw + _i * 8192), 16, 0, 0); } while (0)
; #define PG8_LDA(dst, b, h) do { _Pragma("unroll") for (int m = 0; m < 4; ++m) _Pragma("unroll") for (int k = 0; k < 2; ++k) dst[m][k] = *(const LAS bf16x8*)(lds + PG8_SA(b, h) + aoff + m * 2048 + k * 1024); } while (0)
; #define PG8_LDB(dst, b, h) do { _Pragma("unroll") for (int n = 0; n < 2; ++n) _Pragma("unroll") for (int k = 0; k < 2; ++k) dst[n][k] = *(const LAS bf16x8*)(lds + PG8_SB(b, h) + boff + n * 2048 + k * 1024); } while (0)
; #define PG8_MMA(ai, bj, At, Bt) do { __builtin_amdgcn_s_setprio(1); _Pragma("unroll") for (int m = 0; m < 4; ++m) _Pragma("unroll") for (int n = 0; n < 2; ++n) _Pragma("unroll") for (int k = 0; k < 2; ++k) \
;         acc[ai][bj][m][n] = __builtin_amdgcn_mfma_f32_16x16x32_bf16(Bt[n][k], At[m][k], acc[ai][bj][m][n], 0, 0, 0); __builtin_amdgcn_s_setprio(0); } while (0)
; #define PG8_WAIT_V(n) asm volatile("s_waitcnt vmcnt(" #n ")" ::: "memory")
; #define PG8_WAIT_L(n) asm volatile("s_waitcnt lgkmcnt(" #n ")" ::: "memory")
; #define PG8_BAR __builtin_amdgcn_s_barrier()
; #define PG8_SCHED __builtin_amdgcn_sched_barrier(0)
; template <class Epi, class Sched>
; __device__ __forceinline__ void gemm_stream(LAS unsigned char* lds, const int lda, const int ldb, const Sched& S, const Epi& E, const int wv) {
;     ...
;             const char* a1 = cA + (size_t)(t + 1) * kstep;
;             const char* a2 = last ? nA : cA + (size_t)(t + 2) * kstep; const char* b2 = last ? nB : cB + (size_t)(t + 2) * kstep;
;             const char* a3 = a2 + kstep; const char* b3 = b2 + kstep;
;             PG8_LDB(B0, 0, 0); PG8_LDB(B1, 0, 1); PG8_SCHED; PG8_LDA(At, 0, 0); PG8_STAGE(PG8_SA(1, 1), a1 + hstepA, voffA);
;             PG8_WAIT_V(8); PG8_WAIT_L(0); PG8_BAR; PG8_MMA(0, 0, At, B0); PG8_MMA(0, 1, At, B1); PG8_BAR; PG8_SCHED;
;             PG8_LDA(At, 0, 1); PG8_STAGE(PG8_SB(0, 0), b2, voffB); PG8_STAGE(PG8_SB(0, 1), b2 + hstepB, voffB); PG8_STAGE(PG8_SA(0, 0), a2, voffA);
;             PG8_WAIT_V(8); PG8_WAIT_L(0); PG8_BAR; PG8_MMA(1, 0, At, B0); PG8_MMA(1, 1, At, B1); PG8_BAR; PG8_SCHED;
.LBB0_222:
	s_add_u32 s30, s28, 0xfff80080
	s_addc_u32 s31, s29, -1
	s_add_i32 s38, 0, 0x10000
	s_cmp_eq_u32 s37, 28
	s_cselect_b32 s35, s3, s31
	s_cselect_b32 s34, s21, s30
	s_cselect_b32 s31, s23, s36
	s_cselect_b32 s30, s27, s33
	s_add_i32 s59, 0, 0x14000
	v_add_u32_e32 v140, s38, v163
	v_add_u32_e32 v160, s59, v163
	ds_read_b128 v[128:131], v140
	ds_read_b128 v[132:135], v140 offset:1024
	ds_read_b128 v[136:139], v140 offset:2048
	ds_read_b128 v[140:143], v140 offset:3072
	ds_read_b128 v[156:159], v160
	ds_read_b128 v[166:169], v160 offset:1024
	ds_read_b128 v[170:173], v160 offset:2048
	ds_read_b128 v[174:177], v160 offset:3072
	v_lshl_add_u64 v[160:161], s[28:29], 0, v[152:153]
	s_add_i32 m0, s42, 0xc000
	ds_read_b128 v[178:181], v164
	ds_read_b128 v[182:185], v164 offset:1024
	ds_read_b128 v[186:189], v164 offset:2048
	ds_read_b128 v[190:193], v164 offset:3072
	ds_read_b128 v[200:203], v164 offset:4096
	ds_read_b128 v[204:207], v164 offset:5120
	ds_read_b128 v[208:211], v164 offset:6144
	ds_read_b128 v[212:215], v164 offset:7168
	global_load_lds_dwordx4 v[160:161], off
	v_lshl_add_u64 v[160:161], s[28:29], 0, v[154:155]
	s_add_i32 m0, s42, 0xe000
	s_nop 0
	global_load_lds_dwordx4 v[160:161], off
	s_waitcnt vmcnt(8)
	s_waitcnt lgkmcnt(0)
	s_barrier
	s_setprio 1
	v_mfma_f32_16x16x32_bf16 v[124:127], v[128:131], v[178:181], v[124:127]
	v_mfma_f32_16x16x32_bf16 v[120:123], v[136:139], v[178:181], v[120:123]
	v_mfma_f32_16x16x32_bf16 v[108:111], v[128:131], v[186:189], v[108:111]
	v_mfma_f32_16x16x32_bf16 v[104:107], v[136:139], v[186:189], v[104:107]
	v_mfma_f32_16x16x32_bf16 v[92:95], v[128:131], v[200:203], v[92:95]
	v_mfma_f32_16x16x32_bf16 v[88:91], v[136:139], v[200:203], v[88:91]
	v_mfma_f32_16x16x32_bf16 v[76:79], v[128:131], v[208:211], v[76:79]
	v_mfma_f32_16x16x32_bf16 v[72:75], v[136:139], v[208:211], v[72:75]
	v_mfma_f32_16x16x32_bf16 v[124:127], v[132:135], v[182:185], v[124:127]
	v_mfma_f32_16x16x32_bf16 v[120:123], v[140:143], v[182:185], v[120:123]
	v_mfma_f32_16x16x32_bf16 v[108:111], v[132:135], v[190:193], v[108:111]
	v_mfma_f32_16x16x32_bf16 v[104:107], v[140:143], v[190:193], v[104:107]
	v_mfma_f32_16x16x32_bf16 v[92:95], v[132:135], v[204:207], v[92:95]
	v_mfma_f32_16x16x32_bf16 v[88:91], v[140:143], v[204:207], v[88:91]
	v_mfma_f32_16x16x32_bf16 v[76:79], v[132:135], v[212:215], v[76:79]
	v_mfma_f32_16x16x32_bf16 v[72:75], v[140:143], v[212:215], v[72:75]
	s_setprio 0
	s_setprio 1
	v_mfma_f32_16x16x32_bf16 v[116:119], v[156:159], v[178:181], v[116:119]
	v_mfma_f32_16x16x32_bf16 v[112:115], v[170:173], v[178:181], v[112:115]
	v_mfma_f32_16x16x32_bf16 v[100:103], v[156:159], v[186:189], v[100:103]
	v_mfma_f32_16x16x32_bf16 v[96:99], v[170:173], v[186:189], v[96:99]
	v_mfma_f32_16x16x32_bf16 v[84:87], v[156:159], v[200:203], v[84:87]
	v_mfma_f32_16x16x32_bf16 v[80:83], v[170:173], v[200:203], v[80:83]
	v_mfma_f32_16x16x32_bf16 v[68:71], v[156:159], v[208:211], v[68:71]
	v_mfma_f32_16x16x32_bf16 v[64:67], v[170:173], v[208:211], v[64:67]
	v_mfma_f32_16x16x32_bf16 v[116:119], v[166:169], v[182:185], v[116:119]
	v_mfma_f32_16x16x32_bf16 v[112:115], v[174:177], v[182:185], v[112:115]
	v_mfma_f32_16x16x32_bf16 v[100:103], v[166:169], v[190:193], v[100:103]
	v_mfma_f32_16x16x32_bf16 v[96:99], v[174:177], v[190:193], v[96:99]
	v_mfma_f32_16x16x32_bf16 v[84:87], v[166:169], v[204:207], v[84:87]
	v_mfma_f32_16x16x32_bf16 v[80:83], v[174:177], v[204:207], v[80:83]
	v_mfma_f32_16x16x32_bf16 v[68:71], v[166:169], v[212:215], v[68:71]
	v_mfma_f32_16x16x32_bf16 v[64:67], v[174:177], v[212:215], v[64:67]
	s_setprio 0
	s_barrier
	s_add_i32 s38, s38, s41
	v_lshl_add_u64 v[160:161], s[30:31], 0, v[146:147]
	s_mov_b32 m0, s38
	ds_read_b128 v[178:181], v164 offset:16384
	ds_read_b128 v[182:185], v164 offset:17408
	ds_read_b128 v[186:189], v164 offset:18432
	ds_read_b128 v[190:193], v164 offset:19456
	ds_read_b128 v[200:203], v164 offset:20480
	ds_read_b128 v[204:207], v164 offset:21504
	ds_read_b128 v[208:211], v164 offset:22528
	ds_read_b128 v[212:215], v164 offset:23552
	global_load_lds_dwordx4 v[160:161], off
	s_add_i32 m0, s38, 0x2000
	s_add_u32 s38, s30, 0x20000
	v_lshl_add_u64 v[216:217], s[30:31], 0, v[150:151]
	s_addc_u32 s39, s31, 0
	s_add_i32 s59, s59, s41
	global_load_lds_dwordx4 v[216:217], off
	v_lshl_add_u64 v[218:219], s[38:39], 0, v[146:147]
	s_mov_b32 m0, s59
	v_lshl_add_u64 v[220:221], s[34:35], 0, v[148:149]
	global_load_lds_dwordx4 v[218:219], off
	v_lshl_add_u64 v[218:219], s[38:39], 0, v[150:151]
	s_add_i32 m0, s59, 0x2000
	s_nop 0
	global_load_lds_dwordx4 v[218:219], off
	v_lshl_add_u64 v[218:219], s[34:35], 0, v[144:145]
	s_mov_b32 m0, s42
	s_nop 0
	global_load_lds_dwordx4 v[218:219], off
	s_mov_b32 m0, s43
	s_nop 0
	global_load_lds_dwordx4 v[220:221], off
	s_waitcnt vmcnt(8)
	s_waitcnt lgkmcnt(0)
	s_barrier
; #define PG8_STAGE(bufoff, gbase, voff) do { _Pragma("unroll") for (int _i = 0; _i < 2; ++_i) \
;         __builtin_amdgcn_global_load_lds((const unsigned*)((const char*)(gbase) + (voff)[_i]), (LAS unsigned*)(lds + (bufoff) + ldsw + _i * 8192), 16, 0, 0); } while (0)
; #define PG8_LDA(dst, b, h) do { _Pragma("unroll") for (int m = 0; m < 4; ++m) _Pragma("unroll") for (int k = 0; k < 2; ++k) dst[m][k] = *(const LAS bf16x8*)(lds + PG8_SA(b, h) + aoff + m * 2048 + k * 1024); } while (0)
; #define PG8_LDB(dst, b, h) do { _Pragma("unroll") for (int n = 0; n < 2; ++n) _Pragma("unroll") for (int k = 0; k < 2; ++k) dst[n][k] = *(const LAS bf16x8*)(lds + PG8_SB(b, h) + boff + n * 2048 + k * 1024); } while (0)
; #define PG8_MMA(ai, bj, At, Bt) do { __builtin_amdgcn_s_setprio(1); _Pragma("unroll") for (int m = 0; m < 4; ++m) _Pragma("unroll") for (int n = 0; n < 2; ++n) _Pragma("unroll") for (int k = 0; k < 2; ++k) \
;         acc[ai][bj][m][n] = __builtin_amdgcn_mfma_f32_16x16x32_bf16(Bt[n][k], At[m][k], acc[ai][bj][m][n], 0, 0, 0); __builtin_amdgcn_s_setprio(0); } while (0)
; #define PG8_WAIT_V(n) asm volatile("s_waitcnt vmcnt(" #n ")" ::: "memory")
; #define PG8_WAIT_L(n) asm volatile("s_waitcnt lgkmcnt(" #n ")" ::: "memory")
; #define PG8_BAR __builtin_amdgcn_s_barrier()
; #define PG8_SCHED __builtin_amdgcn_sched_barrier(0)
; template <class Epi, class Sched>
; __device__ __forceinline__ void gemm_stream(LAS unsigned char* lds, const int lda, const int ldb, const Sched& S, const Epi& E, const int wv) {
;     ...
;             PG8_WAIT_V(8); PG8_WAIT_L(0); PG8_BAR; PG8_MMA(1, 0, At, B0); PG8_MMA(1, 1, At, B1); PG8_BAR; PG8_SCHED;
;             PG8_LDB(B0, 1, 0); PG8_LDB(B1, 1, 1); PG8_SCHED; PG8_LDA(At, 1, 0); PG8_STAGE(PG8_SA(0, 1), a2 + hstepA, voffA);
;             PG8_WAIT_V(8); PG8_WAIT_L(0); PG8_BAR; PG8_MMA(0, 0, At, B0); PG8_MMA(0, 1, At, B1); PG8_BAR; PG8_SCHED;
	s_setprio 1
	v_mfma_f32_16x16x32_bf16 v[60:63], v[128:131], v[178:181], v[60:63]
	v_mfma_f32_16x16x32_bf16 v[56:59], v[136:139], v[178:181], v[56:59]
	v_mfma_f32_16x16x32_bf16 v[44:47], v[128:131], v[186:189], v[44:47]
	v_mfma_f32_16x16x32_bf16 v[40:43], v[136:139], v[186:189], v[40:43]
	v_mfma_f32_16x16x32_bf16 v[28:31], v[128:131], v[200:203], v[28:31]
	v_mfma_f32_16x16x32_bf16 v[24:27], v[136:139], v[200:203], v[24:27]
	v_mfma_f32_16x16x32_bf16 v[12:15], v[128:131], v[208:211], v[12:15]
	v_mfma_f32_16x16x32_bf16 v[8:11], v[136:139], v[208:211], v[8:11]
	v_mfma_f32_16x16x32_bf16 v[60:63], v[132:135], v[182:185], v[60:63]
	v_mfma_f32_16x16x32_bf16 v[56:59], v[140:143], v[182:185], v[56:59]
	v_mfma_f32_16x16x32_bf16 v[44:47], v[132:135], v[190:193], v[44:47]
	v_mfma_f32_16x16x32_bf16 v[40:43], v[140:143], v[190:193], v[40:43]
	v_mfma_f32_16x16x32_bf16 v[28:31], v[132:135], v[204:207], v[28:31]
	v_mfma_f32_16x16x32_bf16 v[24:27], v[140:143], v[204:207], v[24:27]
	v_mfma_f32_16x16x32_bf16 v[12:15], v[132:135], v[212:215], v[12:15]
	v_mfma_f32_16x16x32_bf16 v[8:11], v[140:143], v[212:215], v[8:11]
	s_setprio 0
	s_setprio 1
	v_mfma_f32_16x16x32_bf16 v[52:55], v[156:159], v[178:181], v[52:55]
	v_mfma_f32_16x16x32_bf16 v[48:51], v[170:173], v[178:181], v[48:51]
	v_mfma_f32_16x16x32_bf16 v[36:39], v[156:159], v[186:189], v[36:39]
	v_mfma_f32_16x16x32_bf16 v[32:35], v[170:173], v[186:189], v[32:35]
	v_mfma_f32_16x16x32_bf16 v[20:23], v[156:159], v[200:203], v[20:23]
	v_mfma_f32_16x16x32_bf16 v[16:19], v[170:173], v[200:203], v[16:19]
	v_mfma_f32_16x16x32_bf16 v[4:7], v[156:159], v[208:211], v[4:7]
	v_mfma_f32_16x16x32_bf16 v[0:3], v[170:173], v[208:211], v[0:3]
	v_mfma_f32_16x16x32_bf16 v[52:55], v[166:169], v[182:185], v[52:55]
	v_mfma_f32_16x16x32_bf16 v[48:51], v[174:177], v[182:185], v[48:51]
	v_mfma_f32_16x16x32_bf16 v[36:39], v[166:169], v[190:193], v[36:39]
	v_mfma_f32_16x16x32_bf16 v[32:35], v[174:177], v[190:193], v[32:35]
	v_mfma_f32_16x16x32_bf16 v[20:23], v[166:169], v[204:207], v[20:23]
	v_mfma_f32_16x16x32_bf16 v[16:19], v[174:177], v[204:207], v[16:19]
	v_mfma_f32_16x16x32_bf16 v[4:7], v[166:169], v[212:215], v[4:7]
	v_mfma_f32_16x16x32_bf16 v[0:3], v[174:177], v[212:215], v[0:3]
	s_setprio 0
	s_barrier
	s_add_i32 s38, 0, 0x18000
	s_add_i32 s39, 0, 0x1c000
	v_add_u32_e32 v140, s38, v163
	v_add_u32_e32 v165, s39, v163
	ds_read_b128 v[128:131], v140
	ds_read_b128 v[132:135], v140 offset:1024
	ds_read_b128 v[136:139], v140 offset:2048
	ds_read_b128 v[140:143], v140 offset:3072
	ds_read_b128 v[156:159], v165
	ds_read_b128 v[166:169], v165 offset:1024
	ds_read_b128 v[170:173], v165 offset:2048
	ds_read_b128 v[174:177], v165 offset:3072
	s_add_u32 s34, s34, 0x80000
	s_addc_u32 s35, s35, 0
	s_mov_b32 m0, s44
	v_lshl_add_u64 v[222:223], s[34:35], 0, v[144:145]
	ds_read_b128 v[178:181], v164 offset:32768
	ds_read_b128 v[182:185], v164 offset:33792
	ds_read_b128 v[186:189], v164 offset:34816
	ds_read_b128 v[190:193], v164 offset:35840
	ds_read_b128 v[200:203], v164 offset:36864
	ds_read_b128 v[204:207], v164 offset:37888
	ds_read_b128 v[208:211], v164 offset:38912
	ds_read_b128 v[212:215], v164 offset:39936
	global_load_lds_dwordx4 v[222:223], off
	v_lshl_add_u64 v[222:223], s[34:35], 0, v[148:149]
	s_mov_b32 m0, s45
	s_nop 0
	global_load_lds_dwordx4 v[222:223], off
	s_waitcnt vmcnt(8)
	s_waitcnt lgkmcnt(0)
	s_barrier
	s_setprio 1
	v_mfma_f32_16x16x32_bf16 v[124:127], v[128:131], v[178:181], v[124:127]
	v_mfma_f32_16x16x32_bf16 v[120:123], v[136:139], v[178:181], v[120:123]
	v_mfma_f32_16x16x32_bf16 v[108:111], v[128:131], v[186:189], v[108:111]
	v_mfma_f32_16x16x32_bf16 v[104:107], v[136:139], v[186:189], v[104:107]
	v_mfma_f32_16x16x32_bf16 v[92:95], v[128:131], v[200:203], v[92:95]
	v_mfma_f32_16x16x32_bf16 v[88:91], v[136:139], v[200:203], v[88:91]
	v_mfma_f32_16x16x32_bf16 v[76:79], v[128:131], v[208:211], v[76:79]
	v_mfma_f32_16x16x32_bf16 v[72:75], v[136:139], v[208:211], v[72:75]
	v_mfma_f32_16x16x32_bf16 v[124:127], v[132:135], v[182:185], v[124:127]
	v_mfma_f32_16x16x32_bf16 v[120:123], v[140:143], v[182:185], v[120:123]
	v_mfma_f32_16x16x32_bf16 v[108:111], v[132:135], v[190:193], v[108:111]
	v_mfma_f32_16x16x32_bf16 v[104:107], v[140:143], v[190:193], v[104:107]
	v_mfma_f32_16x16x32_bf16 v[92:95], v[132:135], v[204:207], v[92:95]
	v_mfma_f32_16x16x32_bf16 v[88:91], v[140:143], v[204:207], v[88:91]
	v_mfma_f32_16x16x32_bf16 v[76:79], v[132:135], v[212:215], v[76:79]
	v_mfma_f32_16x16x32_bf16 v[72:75], v[140:143], v[212:215], v[72:75]
	s_setprio 0
	s_setprio 1
	v_mfma_f32_16x16x32_bf16 v[116:119], v[156:159], v[178:181], v[116:119]
	v_mfma_f32_16x16x32_bf16 v[112:115], v[170:173], v[178:181], v[112:115]
	v_mfma_f32_16x16x32_bf16 v[100:103], v[156:159], v[186:189], v[100:103]
	v_mfma_f32_16x16x32_bf16 v[96:99], v[170:173], v[186:189], v[96:99]
	v_mfma_f32_16x16x32_bf16 v[84:87], v[156:159], v[200:203], v[84:87]
	v_mfma_f32_16x16x32_bf16 v[80:83], v[170:173], v[200:203], v[80:83]
	v_mfma_f32_16x16x32_bf16 v[68:71], v[156:159], v[208:211], v[68:71]
	v_mfma_f32_16x16x32_bf16 v[64:67], v[170:173], v[208:211], v[64:67]
	v_mfma_f32_16x16x32_bf16 v[116:119], v[166:169], v[182:185], v[116:119]
	v_mfma_f32_16x16x32_bf16 v[112:115], v[174:177], v[182:185], v[112:115]
	v_mfma_f32_16x16x32_bf16 v[100:103], v[166:169], v[190:193], v[100:103]
	v_mfma_f32_16x16x32_bf16 v[96:99], v[174:177], v[190:193], v[96:99]
	v_mfma_f32_16x16x32_bf16 v[84:87], v[166:169], v[204:207], v[84:87]
	v_mfma_f32_16x16x32_bf16 v[80:83], v[174:177], v[204:207], v[80:83]
	v_mfma_f32_16x16x32_bf16 v[68:71], v[166:169], v[212:215], v[68:71]
	v_mfma_f32_16x16x32_bf16 v[64:67], v[174:177], v[212:215], v[64:67]
	s_setprio 0
	s_barrier
; #define PG8_STAGE(bufoff, gbase, voff) do { _Pragma("unroll") for (int _i = 0; _i < 2; ++_i) \
;         __builtin_amdgcn_global_load_lds((const unsigned*)((const char*)(gbase) + (voff)[_i]), (LAS unsigned*)(lds + (bufoff) + ldsw + _i * 8192), 16, 0, 0); } while (0)
; #define PG8_LDA(dst, b, h) do { _Pragma("unroll") for (int m = 0; m < 4; ++m) _Pragma("unroll") for (int k = 0; k < 2; ++k) dst[m][k] = *(const LAS bf16x8*)(lds + PG8_SA(b, h) + aoff + m * 2048 + k * 1024); } while (0)
; #define PG8_MMA(ai, bj, At, Bt) do { __builtin_amdgcn_s_setprio(1); _Pragma("unroll") for (int m = 0; m < 4; ++m) _Pragma("unroll") for (int n = 0; n < 2; ++n) _Pragma("unroll") for (int k = 0; k < 2; ++k) \
;         acc[ai][bj][m][n] = __builtin_amdgcn_mfma_f32_16x16x32_bf16(Bt[n][k], At[m][k], acc[ai][bj][m][n], 0, 0, 0); __builtin_amdgcn_s_setprio(0); } while (0)
; #define PG8_WAIT_V(n) asm volatile("s_waitcnt vmcnt(" #n ")" ::: "memory")
; #define PG8_WAIT_L(n) asm volatile("s_waitcnt lgkmcnt(" #n ")" ::: "memory")
; #define PG8_BAR __builtin_amdgcn_s_barrier()
; #define PG8_SCHED __builtin_amdgcn_sched_barrier(0)
; template <class Epi, class Sched>
; __device__ __forceinline__ void gemm_stream(LAS unsigned char* lds, const int lda, const int ldb, const Sched& S, const Epi& E, const int wv) {
;     ...
;             PG8_LDA(At, 1, 1); PG8_STAGE(PG8_SB(1, 0), b3, voffB); PG8_STAGE(PG8_SB(1, 1), b3 + hstepB, voffB); PG8_STAGE(PG8_SA(1, 0), a3, voffA);
;             PG8_WAIT_V(8); PG8_WAIT_L(0); PG8_BAR; PG8_MMA(1, 0, At, B0); PG8_MMA(1, 1, At, B1); PG8_BAR; PG8_SCHED;
;         }
;         if (wr == 0) PG8_BAR;
	s_add_i32 s34, s38, s41
	v_lshl_add_u64 v[160:161], v[160:161], 0, s[78:79]
	s_mov_b32 m0, s34
	ds_read_b128 v[178:181], v164 offset:49152
	ds_read_b128 v[182:185], v164 offset:50176
	ds_read_b128 v[186:189], v164 offset:51200
	ds_read_b128 v[190:193], v164 offset:52224
	ds_read_b128 v[200:203], v164 offset:53248
	ds_read_b128 v[204:207], v164 offset:54272
	ds_read_b128 v[208:211], v164 offset:55296
	ds_read_b128 v[212:215], v164 offset:56320
	global_load_lds_dwordx4 v[160:161], off
	s_add_i32 m0, s34, 0x2000
	s_add_u32 s30, s30, 0x20080
	v_lshl_add_u64 v[160:161], v[216:217], 0, s[78:79]
	s_addc_u32 s31, s31, 0
	s_add_i32 s34, s39, s41
	global_load_lds_dwordx4 v[160:161], off
	v_lshl_add_u64 v[160:161], s[30:31], 0, v[146:147]
	s_mov_b32 m0, s34
	s_nop 0
	global_load_lds_dwordx4 v[160:161], off
	v_lshl_add_u64 v[160:161], s[30:31], 0, v[150:151]
	s_add_i32 m0, s34, 0x2000
	s_nop 0
	global_load_lds_dwordx4 v[160:161], off
	v_lshl_add_u64 v[160:161], v[218:219], 0, s[78:79]
	s_mov_b32 m0, s49
	s_nop 0
	global_load_lds_dwordx4 v[160:161], off
	v_lshl_add_u64 v[160:161], v[220:221], 0, s[78:79]
	s_mov_b32 m0, s50
	s_nop 0
	global_load_lds_dwordx4 v[160:161], off
	s_waitcnt vmcnt(8)
	s_waitcnt lgkmcnt(0)
	s_barrier
	s_setprio 1
	v_mfma_f32_16x16x32_bf16 v[60:63], v[128:131], v[178:181], v[60:63]
	v_mfma_f32_16x16x32_bf16 v[56:59], v[136:139], v[178:181], v[56:59]
	v_mfma_f32_16x16x32_bf16 v[44:47], v[128:131], v[186:189], v[44:47]
	v_mfma_f32_16x16x32_bf16 v[40:43], v[136:139], v[186:189], v[40:43]
	v_mfma_f32_16x16x32_bf16 v[28:31], v[128:131], v[200:203], v[28:31]
	v_mfma_f32_16x16x32_bf16 v[24:27], v[136:139], v[200:203], v[24:27]
	v_mfma_f32_16x16x32_bf16 v[12:15], v[128:131], v[208:211], v[12:15]
	v_mfma_f32_16x16x32_bf16 v[8:11], v[136:139], v[208:211], v[8:11]
	v_mfma_f32_16x16x32_bf16 v[60:63], v[132:135], v[182:185], v[60:63]
	v_mfma_f32_16x16x32_bf16 v[56:59], v[140:143], v[182:185], v[56:59]
	v_mfma_f32_16x16x32_bf16 v[44:47], v[132:135], v[190:193], v[44:47]
	v_mfma_f32_16x16x32_bf16 v[40:43], v[140:143], v[190:193], v[40:43]
	v_mfma_f32_16x16x32_bf16 v[28:31], v[132:135], v[204:207], v[28:31]
	v_mfma_f32_16x16x32_bf16 v[24:27], v[140:143], v[204:207], v[24:27]
	v_mfma_f32_16x16x32_bf16 v[12:15], v[132:135], v[212:215], v[12:15]
	v_mfma_f32_16x16x32_bf16 v[8:11], v[140:143], v[212:215], v[8:11]
	s_setprio 0
	s_setprio 1
	v_mfma_f32_16x16x32_bf16 v[52:55], v[156:159], v[178:181], v[52:55]
	v_mfma_f32_16x16x32_bf16 v[48:51], v[170:173], v[178:181], v[48:51]
	v_mfma_f32_16x16x32_bf16 v[36:39], v[156:159], v[186:189], v[36:39]
	v_mfma_f32_16x16x32_bf16 v[32:35], v[170:173], v[186:189], v[32:35]
	v_mfma_f32_16x16x32_bf16 v[20:23], v[156:159], v[200:203], v[20:23]
	v_mfma_f32_16x16x32_bf16 v[16:19], v[170:173], v[200:203], v[16:19]
	v_mfma_f32_16x16x32_bf16 v[4:7], v[156:159], v[208:211], v[4:7]
	v_mfma_f32_16x16x32_bf16 v[0:3], v[170:173], v[208:211], v[0:3]
	v_mfma_f32_16x16x32_bf16 v[52:55], v[166:169], v[182:185], v[52:55]
	v_mfma_f32_16x16x32_bf16 v[48:51], v[174:177], v[182:185], v[48:51]
	v_mfma_f32_16x16x32_bf16 v[36:39], v[166:169], v[190:193], v[36:39]
	v_mfma_f32_16x16x32_bf16 v[32:35], v[174:177], v[190:193], v[32:35]
	v_mfma_f32_16x16x32_bf16 v[20:23], v[166:169], v[204:207], v[20:23]
	v_mfma_f32_16x16x32_bf16 v[16:19], v[174:177], v[204:207], v[16:19]
	v_mfma_f32_16x16x32_bf16 v[4:7], v[166:169], v[212:215], v[4:7]
	v_mfma_f32_16x16x32_bf16 v[0:3], v[174:177], v[212:215], v[0:3]
	s_setprio 0
	s_barrier
	s_add_i32 s37, s37, 2
	s_add_u32 s28, s28, 0x100
	s_addc_u32 s29, s29, 0
	s_add_u32 s33, s33, 0x100
	s_addc_u32 s36, s36, 0
	s_cmp_gt_u32 s37, 29
	s_cbranch_scc0 .LBB0_222
	s_and_b64 vcc, exec, s[14:15]
	s_cbranch_vccz .LBB0_225
	s_barrier

; #define PG8_STAGE(bufoff, gbase, voff) do { _Pragma("unroll") for (int _i = 0; _i < 2; ++_i) \
;         __builtin_amdgcn_global_load_lds((const unsigned*)((const char*)(gbase) + (voff)[_i]), (LAS unsigned*)(lds + (bufoff) + ldsw + _i * 8192), 16, 0, 0); } while (0)
; #define PG8_LDA(dst, b, h) do { _Pragma("unroll") for (int m = 0; m < 4; ++m) _Pragma("unroll") for (int k = 0; k < 2; ++k) dst[m][k] = *(const LAS bf16x8*)(lds + PG8_SA(b, h) + aoff + m * 2048 + k * 1024); } while (0)
; #define PG8_LDB(dst, b, h) do { _Pragma("unroll") for (int n = 0; n < 2; ++n) _Pragma("unroll") for (int k = 0; k < 2; ++k) dst[n][k] = *(const LAS bf16x8*)(lds + PG8_SB(b, h) + boff + n * 2048 + k * 1024); } while (0)
; #define PG8_MMA(ai, bj, At, Bt) do { __builtin_amdgcn_s_setprio(1); _Pragma("unroll") for (int m = 0; m < 4; ++m) _Pragma("unroll") for (int n = 0; n < 2; ++n) _Pragma("unroll") for (int k = 0; k < 2; ++k) \
;         acc[ai][bj][m][n] = __builtin_amdgcn_mfma_f32_16x16x32_bf16(Bt[n][k], At[m][k], acc[ai][bj][m][n], 0, 0, 0); __builtin_amdgcn_s_setprio(0); } while (0)
; #define PG8_WAIT_V(n) asm volatile("s_waitcnt vmcnt(" #n ")" ::: "memory")
; #define PG8_WAIT_L(n) asm volatile("s_waitcnt lgkmcnt(" #n ")" ::: "memory")
; #define PG8_BAR __builtin_amdgcn_s_barrier()
; #define PG8_SCHED __builtin_amdgcn_sched_barrier(0)
; template <class Epi, class Sched>
; __device__ __forceinline__ void gemm_stream(LAS unsigned char* lds, const int lda, const int ldb, const Sched& S, const Epi& E, const int wv) {
;     ...
;             const char* a1 = cA + (size_t)(t + 1) * kstep;
;             const char* a2 = last ? nA : cA + (size_t)(t + 2) * kstep; const char* b2 = last ? nB : cB + (size_t)(t + 2) * kstep;
;             const char* a3 = a2 + kstep; const char* b3 = b2 + kstep;
;             PG8_LDB(B0, 0, 0); PG8_LDB(B1, 0, 1); PG8_SCHED; PG8_LDA(At, 0, 0); PG8_STAGE(PG8_SA(1, 1), a1 + hstepA, voffA);
;             PG8_WAIT_V(8); PG8_WAIT_L(0); PG8_BAR; PG8_MMA(0, 0, At, B0); PG8_MMA(0, 1, At, B1); PG8_BAR; PG8_SCHED;
;             PG8_LDA(At, 0, 1); PG8_STAGE(PG8_SB(0, 0), b2, voffB); PG8_STAGE(PG8_SB(0, 1), b2 + hstepB, voffB); PG8_STAGE(PG8_SA(0, 0), a2, voffA);
;             PG8_WAIT_V(8); PG8_WAIT_L(0); PG8_BAR; PG8_MMA(1, 0, At, B0); PG8_MMA(1, 1, At, B1); PG8_BAR; PG8_SCHED;
.LBB0_496:
	s_add_i32 s63, s24, 2
	s_add_u32 s22, s4, 0x100
	s_addc_u32 s23, s5, 0
	s_add_i32 s66, 0, 0x10000
	s_cmp_eq_u32 s60, s24
	s_cselect_b32 s27, s33, s23
	s_cselect_b32 s26, s57, s22
	v_add_u32_e32 v120, s66, v235
	s_cselect_b32 s25, s58, s62
	s_cselect_b32 s24, s59, s61
	s_add_i32 s67, 0, 0x14000
	ds_read_b128 v[130:133], v120
	ds_read_b128 v[134:137], v120 offset:1024
	ds_read_b128 v[138:141], v120 offset:2048
	ds_read_b128 v[142:145], v120 offset:3072
	v_add_u32_e32 v120, s67, v235
	ds_read_b128 v[146:149], v120
	ds_read_b128 v[150:153], v120 offset:1024
	ds_read_b128 v[154:157], v120 offset:2048
	ds_read_b128 v[158:161], v120 offset:3072
	v_lshl_add_u64 v[120:121], s[4:5], 0, v[208:209]
	s_add_i32 m0, s36, 0xc000
	ds_read_b128 v[162:165], v236
	ds_read_b128 v[166:169], v236 offset:1024
	ds_read_b128 v[170:173], v236 offset:2048
	ds_read_b128 v[174:177], v236 offset:3072
	ds_read_b128 v[178:181], v236 offset:4096
	ds_read_b128 v[182:185], v236 offset:5120
	ds_read_b128 v[186:189], v236 offset:6144
	ds_read_b128 v[190:193], v236 offset:7168
	global_load_lds_dwordx4 v[120:121], off
	v_lshl_add_u64 v[120:121], s[4:5], 0, v[210:211]
	s_add_i32 m0, s36, 0xe000
	s_nop 0
	global_load_lds_dwordx4 v[120:121], off
	s_waitcnt vmcnt(8)
	s_waitcnt lgkmcnt(0)
	s_barrier
	s_setprio 1
	v_mfma_f32_16x16x32_bf16 v[126:129], v[130:133], v[162:165], v[126:129]
	v_mfma_f32_16x16x32_bf16 v[120:123], v[138:141], v[162:165], v[122:125]
	v_mfma_f32_16x16x32_bf16 v[116:119], v[130:133], v[170:173], v[116:119]
	v_mfma_f32_16x16x32_bf16 v[112:115], v[138:141], v[170:173], v[112:115]
	v_mfma_f32_16x16x32_bf16 v[100:103], v[130:133], v[178:181], v[100:103]
	v_mfma_f32_16x16x32_bf16 v[96:99], v[138:141], v[178:181], v[96:99]
	v_mfma_f32_16x16x32_bf16 v[84:87], v[130:133], v[186:189], v[84:87]
	v_mfma_f32_16x16x32_bf16 v[80:83], v[138:141], v[186:189], v[80:83]
	v_mfma_f32_16x16x32_bf16 v[126:129], v[134:137], v[166:169], v[126:129]
	v_mfma_f32_16x16x32_bf16 v[120:123], v[142:145], v[166:169], v[120:123]
	v_mfma_f32_16x16x32_bf16 v[116:119], v[134:137], v[174:177], v[116:119]
	v_mfma_f32_16x16x32_bf16 v[112:115], v[142:145], v[174:177], v[112:115]
	v_mfma_f32_16x16x32_bf16 v[100:103], v[134:137], v[182:185], v[100:103]
	v_mfma_f32_16x16x32_bf16 v[96:99], v[142:145], v[182:185], v[96:99]
	v_mfma_f32_16x16x32_bf16 v[84:87], v[134:137], v[190:193], v[84:87]
	v_mfma_f32_16x16x32_bf16 v[80:83], v[142:145], v[190:193], v[80:83]
	s_setprio 0
	s_setprio 1
	v_mfma_f32_16x16x32_bf16 v[108:111], v[146:149], v[162:165], v[108:111]
	v_mfma_f32_16x16x32_bf16 v[104:107], v[154:157], v[162:165], v[104:107]
	v_mfma_f32_16x16x32_bf16 v[92:95], v[146:149], v[170:173], v[92:95]
	v_mfma_f32_16x16x32_bf16 v[88:91], v[154:157], v[170:173], v[88:91]
	v_mfma_f32_16x16x32_bf16 v[76:79], v[146:149], v[178:181], v[76:79]
	v_mfma_f32_16x16x32_bf16 v[72:75], v[154:157], v[178:181], v[72:75]
	v_mfma_f32_16x16x32_bf16 v[68:71], v[146:149], v[186:189], v[68:71]
	v_mfma_f32_16x16x32_bf16 v[64:67], v[154:157], v[186:189], v[64:67]
	v_mfma_f32_16x16x32_bf16 v[108:111], v[150:153], v[166:169], v[108:111]
	v_mfma_f32_16x16x32_bf16 v[104:107], v[158:161], v[166:169], v[104:107]
	v_mfma_f32_16x16x32_bf16 v[92:95], v[150:153], v[174:177], v[92:95]
	v_mfma_f32_16x16x32_bf16 v[88:91], v[158:161], v[174:177], v[88:91]
	v_mfma_f32_16x16x32_bf16 v[76:79], v[150:153], v[182:185], v[76:79]
	v_mfma_f32_16x16x32_bf16 v[72:75], v[158:161], v[182:185], v[72:75]
	v_mfma_f32_16x16x32_bf16 v[68:71], v[150:153], v[190:193], v[68:71]
	v_mfma_f32_16x16x32_bf16 v[64:67], v[158:161], v[190:193], v[64:67]
	s_setprio 0
	s_barrier
	s_add_i32 s4, s66, s35
	v_lshl_add_u64 v[196:197], s[24:25], 0, v[202:203]
	s_mov_b32 m0, s4
	ds_read_b128 v[162:165], v236 offset:16384
	ds_read_b128 v[166:169], v236 offset:17408
	ds_read_b128 v[170:173], v236 offset:18432
	ds_read_b128 v[174:177], v236 offset:19456
	ds_read_b128 v[178:181], v236 offset:20480
	ds_read_b128 v[182:185], v236 offset:21504
	ds_read_b128 v[186:189], v236 offset:22528
	ds_read_b128 v[190:193], v236 offset:23552
	global_load_lds_dwordx4 v[196:197], off
	s_add_i32 m0, s4, 0x2000
	s_add_u32 s4, s24, 0x20000
	v_lshl_add_u64 v[198:199], s[24:25], 0, v[206:207]
	s_addc_u32 s5, s25, 0
	s_add_i32 s66, s67, s35
	global_load_lds_dwordx4 v[198:199], off
	v_lshl_add_u64 v[124:125], s[4:5], 0, v[202:203]
	s_mov_b32 m0, s66
	v_lshl_add_u64 v[212:213], s[26:27], 0, v[200:201]
	global_load_lds_dwordx4 v[124:125], off
	v_lshl_add_u64 v[124:125], s[4:5], 0, v[206:207]
	s_add_i32 m0, s66, 0x2000
	v_lshl_add_u64 v[214:215], s[26:27], 0, v[204:205]
	global_load_lds_dwordx4 v[124:125], off
	s_mov_b32 m0, s36
	s_nop 0
	global_load_lds_dwordx4 v[212:213], off
	s_mov_b32 m0, s37
	s_nop 0
	global_load_lds_dwordx4 v[214:215], off
	s_waitcnt vmcnt(8)
	s_waitcnt lgkmcnt(0)
	s_barrier
; #define PG8_STAGE(bufoff, gbase, voff) do { _Pragma("unroll") for (int _i = 0; _i < 2; ++_i) \
;         __builtin_amdgcn_global_load_lds((const unsigned*)((const char*)(gbase) + (voff)[_i]), (LAS unsigned*)(lds + (bufoff) + ldsw + _i * 8192), 16, 0, 0); } while (0)
; #define PG8_LDA(dst, b, h) do { _Pragma("unroll") for (int m = 0; m < 4; ++m) _Pragma("unroll") for (int k = 0; k < 2; ++k) dst[m][k] = *(const LAS bf16x8*)(lds + PG8_SA(b, h) + aoff + m * 2048 + k * 1024); } while (0)
; #define PG8_LDB(dst, b, h) do { _Pragma("unroll") for (int n = 0; n < 2; ++n) _Pragma("unroll") for (int k = 0; k < 2; ++k) dst[n][k] = *(const LAS bf16x8*)(lds + PG8_SB(b, h) + boff + n * 2048 + k * 1024); } while (0)
; #define PG8_MMA(ai, bj, At, Bt) do { __builtin_amdgcn_s_setprio(1); _Pragma("unroll") for (int m = 0; m < 4; ++m) _Pragma("unroll") for (int n = 0; n < 2; ++n) _Pragma("unroll") for (int k = 0; k < 2; ++k) \
;         acc[ai][bj][m][n] = __builtin_amdgcn_mfma_f32_16x16x32_bf16(Bt[n][k], At[m][k], acc[ai][bj][m][n], 0, 0, 0); __builtin_amdgcn_s_setprio(0); } while (0)
; #define PG8_WAIT_V(n) asm volatile("s_waitcnt vmcnt(" #n ")" ::: "memory")
; #define PG8_WAIT_L(n) asm volatile("s_waitcnt lgkmcnt(" #n ")" ::: "memory")
; #define PG8_BAR __builtin_amdgcn_s_barrier()
; #define PG8_SCHED __builtin_amdgcn_sched_barrier(0)
; template <class Epi, class Sched>
; __device__ __forceinline__ void gemm_stream(LAS unsigned char* lds, const int lda, const int ldb, const Sched& S, const Epi& E, const int wv) {
;     ...
;             PG8_WAIT_V(8); PG8_WAIT_L(0); PG8_BAR; PG8_MMA(1, 0, At, B0); PG8_MMA(1, 1, At, B1); PG8_BAR; PG8_SCHED;
;             PG8_LDB(B0, 1, 0); PG8_LDB(B1, 1, 1); PG8_SCHED; PG8_LDA(At, 1, 0); PG8_STAGE(PG8_SA(0, 1), a2 + hstepA, voffA);
;             PG8_WAIT_V(8); PG8_WAIT_L(0); PG8_BAR; PG8_MMA(0, 0, At, B0); PG8_MMA(0, 1, At, B1); PG8_BAR; PG8_SCHED;
	s_setprio 1
	v_mfma_f32_16x16x32_bf16 v[60:63], v[130:133], v[162:165], v[60:63]
	v_mfma_f32_16x16x32_bf16 v[56:59], v[138:141], v[162:165], v[56:59]
	v_mfma_f32_16x16x32_bf16 v[52:55], v[130:133], v[170:173], v[52:55]
	v_mfma_f32_16x16x32_bf16 v[48:51], v[138:141], v[170:173], v[48:51]
	v_mfma_f32_16x16x32_bf16 v[36:39], v[130:133], v[178:181], v[36:39]
	v_mfma_f32_16x16x32_bf16 v[32:35], v[138:141], v[178:181], v[32:35]
	v_mfma_f32_16x16x32_bf16 v[20:23], v[130:133], v[186:189], v[20:23]
	v_mfma_f32_16x16x32_bf16 v[16:19], v[138:141], v[186:189], v[16:19]
	v_mfma_f32_16x16x32_bf16 v[60:63], v[134:137], v[166:169], v[60:63]
	v_mfma_f32_16x16x32_bf16 v[56:59], v[142:145], v[166:169], v[56:59]
	v_mfma_f32_16x16x32_bf16 v[52:55], v[134:137], v[174:177], v[52:55]
	v_mfma_f32_16x16x32_bf16 v[48:51], v[142:145], v[174:177], v[48:51]
	v_mfma_f32_16x16x32_bf16 v[36:39], v[134:137], v[182:185], v[36:39]
	v_mfma_f32_16x16x32_bf16 v[32:35], v[142:145], v[182:185], v[32:35]
	v_mfma_f32_16x16x32_bf16 v[20:23], v[134:137], v[190:193], v[20:23]
	v_mfma_f32_16x16x32_bf16 v[16:19], v[142:145], v[190:193], v[16:19]
	s_setprio 0
	s_setprio 1
	v_mfma_f32_16x16x32_bf16 v[44:47], v[146:149], v[162:165], v[44:47]
	v_mfma_f32_16x16x32_bf16 v[40:43], v[154:157], v[162:165], v[40:43]
	v_mfma_f32_16x16x32_bf16 v[28:31], v[146:149], v[170:173], v[28:31]
	v_mfma_f32_16x16x32_bf16 v[24:27], v[154:157], v[170:173], v[24:27]
	v_mfma_f32_16x16x32_bf16 v[12:15], v[146:149], v[178:181], v[12:15]
	v_mfma_f32_16x16x32_bf16 v[8:11], v[154:157], v[178:181], v[8:11]
	v_mfma_f32_16x16x32_bf16 v[4:7], v[146:149], v[186:189], v[4:7]
	v_mfma_f32_16x16x32_bf16 v[0:3], v[154:157], v[186:189], v[0:3]
	v_mfma_f32_16x16x32_bf16 v[44:47], v[150:153], v[166:169], v[44:47]
	v_mfma_f32_16x16x32_bf16 v[40:43], v[158:161], v[166:169], v[40:43]
	v_mfma_f32_16x16x32_bf16 v[28:31], v[150:153], v[174:177], v[28:31]
	v_mfma_f32_16x16x32_bf16 v[24:27], v[158:161], v[174:177], v[24:27]
	v_mfma_f32_16x16x32_bf16 v[12:15], v[150:153], v[182:185], v[12:15]
	v_mfma_f32_16x16x32_bf16 v[8:11], v[158:161], v[182:185], v[8:11]
	v_mfma_f32_16x16x32_bf16 v[4:7], v[150:153], v[190:193], v[4:7]
	v_mfma_f32_16x16x32_bf16 v[0:3], v[158:161], v[190:193], v[0:3]
	s_setprio 0
	s_barrier
	s_add_i32 s66, 0, 0x18000
	v_add_u32_e32 v124, s66, v235
	s_add_i32 s67, 0, 0x1c000
	ds_read_b128 v[130:133], v124
	ds_read_b128 v[134:137], v124 offset:1024
	ds_read_b128 v[138:141], v124 offset:2048
	ds_read_b128 v[142:145], v124 offset:3072
	v_add_u32_e32 v124, s67, v235
	ds_read_b128 v[146:149], v124
	ds_read_b128 v[150:153], v124 offset:1024
	ds_read_b128 v[154:157], v124 offset:2048
	ds_read_b128 v[158:161], v124 offset:3072
	s_add_u32 s4, s26, 0x480000
	s_addc_u32 s5, s27, 0
	s_mov_b32 m0, s38
	v_lshl_add_u64 v[124:125], s[4:5], 0, v[200:201]
	ds_read_b128 v[162:165], v236 offset:32768
	ds_read_b128 v[166:169], v236 offset:33792
	ds_read_b128 v[170:173], v236 offset:34816
	ds_read_b128 v[174:177], v236 offset:35840
	ds_read_b128 v[178:181], v236 offset:36864
	ds_read_b128 v[182:185], v236 offset:37888
	ds_read_b128 v[186:189], v236 offset:38912
	ds_read_b128 v[190:193], v236 offset:39936
	global_load_lds_dwordx4 v[124:125], off
	v_lshl_add_u64 v[124:125], s[4:5], 0, v[204:205]
	s_mov_b32 m0, s39
	s_nop 0
	global_load_lds_dwordx4 v[124:125], off
	s_waitcnt vmcnt(8)
	s_waitcnt lgkmcnt(0)
	s_barrier
	s_setprio 1
	v_mfma_f32_16x16x32_bf16 v[124:127], v[130:133], v[162:165], v[126:129]
	v_mfma_f32_16x16x32_bf16 v[120:123], v[138:141], v[162:165], v[120:123]
	v_mfma_f32_16x16x32_bf16 v[116:119], v[130:133], v[170:173], v[116:119]
	v_mfma_f32_16x16x32_bf16 v[112:115], v[138:141], v[170:173], v[112:115]
	v_mfma_f32_16x16x32_bf16 v[100:103], v[130:133], v[178:181], v[100:103]
	v_mfma_f32_16x16x32_bf16 v[96:99], v[138:141], v[178:181], v[96:99]
	v_mfma_f32_16x16x32_bf16 v[84:87], v[130:133], v[186:189], v[84:87]
	v_mfma_f32_16x16x32_bf16 v[80:83], v[138:141], v[186:189], v[80:83]
	v_mfma_f32_16x16x32_bf16 v[126:129], v[134:137], v[166:169], v[124:127]
	v_mfma_f32_16x16x32_bf16 v[122:125], v[142:145], v[166:169], v[120:123]
	v_mfma_f32_16x16x32_bf16 v[116:119], v[134:137], v[174:177], v[116:119]
	v_mfma_f32_16x16x32_bf16 v[112:115], v[142:145], v[174:177], v[112:115]
	v_mfma_f32_16x16x32_bf16 v[100:103], v[134:137], v[182:185], v[100:103]
	v_mfma_f32_16x16x32_bf16 v[96:99], v[142:145], v[182:185], v[96:99]
	v_mfma_f32_16x16x32_bf16 v[84:87], v[134:137], v[190:193], v[84:87]
	v_mfma_f32_16x16x32_bf16 v[80:83], v[142:145], v[190:193], v[80:83]
	s_setprio 0
	s_setprio 1
	v_mfma_f32_16x16x32_bf16 v[108:111], v[146:149], v[162:165], v[108:111]
	v_mfma_f32_16x16x32_bf16 v[104:107], v[154:157], v[162:165], v[104:107]
	v_mfma_f32_16x16x32_bf16 v[92:95], v[146:149], v[170:173], v[92:95]
	v_mfma_f32_16x16x32_bf16 v[88:91], v[154:157], v[170:173], v[88:91]
	v_mfma_f32_16x16x32_bf16 v[76:79], v[146:149], v[178:181], v[76:79]
	v_mfma_f32_16x16x32_bf16 v[72:75], v[154:157], v[178:181], v[72:75]
	v_mfma_f32_16x16x32_bf16 v[68:71], v[146:149], v[186:189], v[68:71]
	v_mfma_f32_16x16x32_bf16 v[64:67], v[154:157], v[186:189], v[64:67]
	v_mfma_f32_16x16x32_bf16 v[108:111], v[150:153], v[166:169], v[108:111]
	v_mfma_f32_16x16x32_bf16 v[104:107], v[158:161], v[166:169], v[104:107]
	v_mfma_f32_16x16x32_bf16 v[92:95], v[150:153], v[174:177], v[92:95]
	v_mfma_f32_16x16x32_bf16 v[88:91], v[158:161], v[174:177], v[88:91]
	v_mfma_f32_16x16x32_bf16 v[76:79], v[150:153], v[182:185], v[76:79]
	v_mfma_f32_16x16x32_bf16 v[72:75], v[158:161], v[182:185], v[72:75]
	v_mfma_f32_16x16x32_bf16 v[68:71], v[150:153], v[190:193], v[68:71]
	v_mfma_f32_16x16x32_bf16 v[64:67], v[158:161], v[190:193], v[64:67]
	s_setprio 0
	s_barrier
; #define PG8_STAGE(bufoff, gbase, voff) do { _Pragma("unroll") for (int _i = 0; _i < 2; ++_i) \
;         __builtin_amdgcn_global_load_lds((const unsigned*)((const char*)(gbase) + (voff)[_i]), (LAS unsigned*)(lds + (bufoff) + ldsw + _i * 8192), 16, 0, 0); } while (0)
; #define PG8_LDA(dst, b, h) do { _Pragma("unroll") for (int m = 0; m < 4; ++m) _Pragma("unroll") for (int k = 0; k < 2; ++k) dst[m][k] = *(const LAS bf16x8*)(lds + PG8_SA(b, h) + aoff + m * 2048 + k * 1024); } while (0)
; #define PG8_MMA(ai, bj, At, Bt) do { __builtin_amdgcn_s_setprio(1); _Pragma("unroll") for (int m = 0; m < 4; ++m) _Pragma("unroll") for (int n = 0; n < 2; ++n) _Pragma("unroll") for (int k = 0; k < 2; ++k) \
;         acc[ai][bj][m][n] = __builtin_amdgcn_mfma_f32_16x16x32_bf16(Bt[n][k], At[m][k], acc[ai][bj][m][n], 0, 0, 0); __builtin_amdgcn_s_setprio(0); } while (0)
; #define PG8_WAIT_V(n) asm volatile("s_waitcnt vmcnt(" #n ")" ::: "memory")
; #define PG8_WAIT_L(n) asm volatile("s_waitcnt lgkmcnt(" #n ")" ::: "memory")
; #define PG8_BAR __builtin_amdgcn_s_barrier()
; #define PG8_SCHED __builtin_amdgcn_sched_barrier(0)
; template <class Epi, class Sched>
; __device__ __forceinline__ void gemm_stream(LAS unsigned char* lds, const int lda, const int ldb, const Sched& S, const Epi& E, const int wv) {
;     ...
;             PG8_LDA(At, 1, 1); PG8_STAGE(PG8_SB(1, 0), b3, voffB); PG8_STAGE(PG8_SB(1, 1), b3 + hstepB, voffB); PG8_STAGE(PG8_SA(1, 0), a3, voffA);
;             PG8_WAIT_V(8); PG8_WAIT_L(0); PG8_BAR; PG8_MMA(1, 0, At, B0); PG8_MMA(1, 1, At, B1); PG8_BAR; PG8_SCHED;
;         }
;         if (wr == 0) PG8_BAR;
	s_add_i32 s4, s66, s35
	v_lshl_add_u64 v[120:121], v[196:197], 0, s[78:79]
	s_mov_b32 m0, s4
	ds_read_b128 v[162:165], v236 offset:49152
	ds_read_b128 v[166:169], v236 offset:50176
	ds_read_b128 v[170:173], v236 offset:51200
	ds_read_b128 v[174:177], v236 offset:52224
	ds_read_b128 v[178:181], v236 offset:53248
	ds_read_b128 v[182:185], v236 offset:54272
	ds_read_b128 v[186:189], v236 offset:55296
	ds_read_b128 v[190:193], v236 offset:56320
	global_load_lds_dwordx4 v[120:121], off
	s_add_i32 m0, s4, 0x2000
	s_add_u32 s4, s24, 0x20080
	v_lshl_add_u64 v[120:121], v[198:199], 0, s[78:79]
	s_addc_u32 s5, s25, 0
	s_add_i32 s24, s67, s35
	global_load_lds_dwordx4 v[120:121], off
	v_lshl_add_u64 v[120:121], s[4:5], 0, v[202:203]
	s_mov_b32 m0, s24
	s_nop 0
	global_load_lds_dwordx4 v[120:121], off
	v_lshl_add_u64 v[120:121], s[4:5], 0, v[206:207]
	s_add_i32 m0, s24, 0x2000
	s_nop 0
	global_load_lds_dwordx4 v[120:121], off
	v_lshl_add_u64 v[120:121], v[212:213], 0, s[78:79]
	s_mov_b32 m0, s43
	s_nop 0
	global_load_lds_dwordx4 v[120:121], off
	v_lshl_add_u64 v[120:121], v[214:215], 0, s[78:79]
	s_mov_b32 m0, s44
	s_nop 0
	global_load_lds_dwordx4 v[120:121], off
	s_waitcnt vmcnt(8)
	s_waitcnt lgkmcnt(0)
	s_barrier
	s_setprio 1
	v_mfma_f32_16x16x32_bf16 v[60:63], v[130:133], v[162:165], v[60:63]
	v_mfma_f32_16x16x32_bf16 v[56:59], v[138:141], v[162:165], v[56:59]
	v_mfma_f32_16x16x32_bf16 v[52:55], v[130:133], v[170:173], v[52:55]
	v_mfma_f32_16x16x32_bf16 v[48:51], v[138:141], v[170:173], v[48:51]
	v_mfma_f32_16x16x32_bf16 v[36:39], v[130:133], v[178:181], v[36:39]
	v_mfma_f32_16x16x32_bf16 v[32:35], v[138:141], v[178:181], v[32:35]
	v_mfma_f32_16x16x32_bf16 v[20:23], v[130:133], v[186:189], v[20:23]
	v_mfma_f32_16x16x32_bf16 v[16:19], v[138:141], v[186:189], v[16:19]
	v_mfma_f32_16x16x32_bf16 v[60:63], v[134:137], v[166:169], v[60:63]
	v_mfma_f32_16x16x32_bf16 v[56:59], v[142:145], v[166:169], v[56:59]
	v_mfma_f32_16x16x32_bf16 v[52:55], v[134:137], v[174:177], v[52:55]
	v_mfma_f32_16x16x32_bf16 v[48:51], v[142:145], v[174:177], v[48:51]
	v_mfma_f32_16x16x32_bf16 v[36:39], v[134:137], v[182:185], v[36:39]
	v_mfma_f32_16x16x32_bf16 v[32:35], v[142:145], v[182:185], v[32:35]
	v_mfma_f32_16x16x32_bf16 v[20:23], v[134:137], v[190:193], v[20:23]
	v_mfma_f32_16x16x32_bf16 v[16:19], v[142:145], v[190:193], v[16:19]
	s_setprio 0
	s_setprio 1
	v_mfma_f32_16x16x32_bf16 v[44:47], v[146:149], v[162:165], v[44:47]
	v_mfma_f32_16x16x32_bf16 v[40:43], v[154:157], v[162:165], v[40:43]
	v_mfma_f32_16x16x32_bf16 v[28:31], v[146:149], v[170:173], v[28:31]
	v_mfma_f32_16x16x32_bf16 v[24:27], v[154:157], v[170:173], v[24:27]
	v_mfma_f32_16x16x32_bf16 v[12:15], v[146:149], v[178:181], v[12:15]
	v_mfma_f32_16x16x32_bf16 v[8:11], v[154:157], v[178:181], v[8:11]
	v_mfma_f32_16x16x32_bf16 v[4:7], v[146:149], v[186:189], v[4:7]
	v_mfma_f32_16x16x32_bf16 v[0:3], v[154:157], v[186:189], v[0:3]
	v_mfma_f32_16x16x32_bf16 v[44:47], v[150:153], v[166:169], v[44:47]
	v_mfma_f32_16x16x32_bf16 v[40:43], v[158:161], v[166:169], v[40:43]
	v_mfma_f32_16x16x32_bf16 v[28:31], v[150:153], v[174:177], v[28:31]
	v_mfma_f32_16x16x32_bf16 v[24:27], v[158:161], v[174:177], v[24:27]
	v_mfma_f32_16x16x32_bf16 v[12:15], v[150:153], v[182:185], v[12:15]
	v_mfma_f32_16x16x32_bf16 v[8:11], v[158:161], v[182:185], v[8:11]
	v_mfma_f32_16x16x32_bf16 v[4:7], v[150:153], v[190:193], v[4:7]
	v_mfma_f32_16x16x32_bf16 v[0:3], v[158:161], v[190:193], v[0:3]
	s_setprio 0
	s_barrier
	s_add_u32 s61, s61, 0x100
	s_addc_u32 s62, s62, 0
	s_cmp_ge_i32 s63, s56
	s_mov_b64 s[4:5], s[22:23]
	s_mov_b32 s24, s63
	s_cbranch_scc0 .LBB0_496
	v_mov_b32_e32 v244, 0x3d800000
	s_and_b64 vcc, exec, s[12:13]
	s_cbranch_vccz .LBB0_499
	s_barrier

; #define PG8_STAGE(bufoff, gbase, voff) do { _Pragma("unroll") for (int _i = 0; _i < 2; ++_i) \
;         __builtin_amdgcn_global_load_lds((const unsigned*)((const char*)(gbase) + (voff)[_i]), (LAS unsigned*)(lds + (bufoff) + ldsw + _i * 8192), 16, 0, 0); } while (0)
; #define PG8_LDA(dst, b, h) do { _Pragma("unroll") for (int m = 0; m < 4; ++m) _Pragma("unroll") for (int k = 0; k < 2; ++k) dst[m][k] = *(const LAS bf16x8*)(lds + PG8_SA(b, h) + aoff + m * 2048 + k * 1024); } while (0)
; #define PG8_LDB(dst, b, h) do { _Pragma("unroll") for (int n = 0; n < 2; ++n) _Pragma("unroll") for (int k = 0; k < 2; ++k) dst[n][k] = *(const LAS bf16x8*)(lds + PG8_SB(b, h) + boff + n * 2048 + k * 1024); } while (0)
; #define PG8_MMA(ai, bj, At, Bt) do { __builtin_amdgcn_s_setprio(1); _Pragma("unroll") for (int m = 0; m < 4; ++m) _Pragma("unroll") for (int n = 0; n < 2; ++n) _Pragma("unroll") for (int k = 0; k < 2; ++k) \
;         acc[ai][bj][m][n] = __builtin_amdgcn_mfma_f32_16x16x32_bf16(Bt[n][k], At[m][k], acc[ai][bj][m][n], 0, 0, 0); __builtin_amdgcn_s_setprio(0); } while (0)
; #define PG8_WAIT_V(n) asm volatile("s_waitcnt vmcnt(" #n ")" ::: "memory")
; #define PG8_WAIT_L(n) asm volatile("s_waitcnt lgkmcnt(" #n ")" ::: "memory")
; #define PG8_BAR __builtin_amdgcn_s_barrier()
; #define PG8_SCHED __builtin_amdgcn_sched_barrier(0)
; template <class Epi, class Sched>
; __device__ __forceinline__ void gemm_stream(LAS unsigned char* lds, const int lda, const int ldb, const Sched& S, const Epi& E, const int wv) {
;     ...
;             const char* a1 = cA + (size_t)(t + 1) * kstep;
;             const char* a2 = last ? nA : cA + (size_t)(t + 2) * kstep; const char* b2 = last ? nB : cB + (size_t)(t + 2) * kstep;
;             const char* a3 = a2 + kstep; const char* b3 = b2 + kstep;
;             PG8_LDB(B0, 0, 0); PG8_LDB(B1, 0, 1); PG8_SCHED; PG8_LDA(At, 0, 0); PG8_STAGE(PG8_SA(1, 1), a1 + hstepA, voffA);
;             PG8_WAIT_V(8); PG8_WAIT_L(0); PG8_BAR; PG8_MMA(0, 0, At, B0); PG8_MMA(0, 1, At, B1); PG8_BAR; PG8_SCHED;
;             PG8_LDA(At, 0, 1); PG8_STAGE(PG8_SB(0, 0), b2, voffB); PG8_STAGE(PG8_SB(0, 1), b2 + hstepB, voffB); PG8_STAGE(PG8_SA(0, 0), a2, voffA);
;             PG8_WAIT_V(8); PG8_WAIT_L(0); PG8_BAR; PG8_MMA(1, 0, At, B0); PG8_MMA(1, 1, At, B1); PG8_BAR; PG8_SCHED;
.LBB0_600:
	s_add_u32 s22, s20, 0xfff80080
	s_addc_u32 s23, s21, -1
	s_add_i32 s47, 0, 0x10000
	s_cmp_eq_u32 s46, 28
	s_cselect_b32 s25, s17, s23
	s_cselect_b32 s24, s16, s22
	s_cselect_b32 s23, s19, s15
	s_cselect_b32 s22, s18, s13
	s_add_i32 s50, 0, 0x14000
	v_add_u32_e32 v140, s47, v165
	v_add_u32_e32 v167, s50, v165
	ds_read_b128 v[128:131], v140
	ds_read_b128 v[132:135], v140 offset:1024
	ds_read_b128 v[136:139], v140 offset:2048
	ds_read_b128 v[140:143], v140 offset:3072
	ds_read_b128 v[156:159], v167
	ds_read_b128 v[160:163], v167 offset:1024
	ds_read_b128 v[168:171], v167 offset:2048
	ds_read_b128 v[172:175], v167 offset:3072
	v_lshl_add_u64 v[192:193], s[20:21], 0, v[152:153]
	s_add_i32 m0, s31, 0xc000
	ds_read_b128 v[176:179], v166
	ds_read_b128 v[180:183], v166 offset:1024
	ds_read_b128 v[184:187], v166 offset:2048
	ds_read_b128 v[188:191], v166 offset:3072
	ds_read_b128 v[200:203], v166 offset:4096
	ds_read_b128 v[204:207], v166 offset:5120
	ds_read_b128 v[208:211], v166 offset:6144
	ds_read_b128 v[212:215], v166 offset:7168
	global_load_lds_dwordx4 v[192:193], off
	v_lshl_add_u64 v[192:193], s[20:21], 0, v[154:155]
	s_add_i32 m0, s31, 0xe000
	s_nop 0
	global_load_lds_dwordx4 v[192:193], off
	s_waitcnt vmcnt(8)
	s_waitcnt lgkmcnt(0)
	s_barrier
	s_setprio 1
	v_mfma_f32_16x16x32_bf16 v[124:127], v[128:131], v[176:179], v[124:127]
	v_mfma_f32_16x16x32_bf16 v[120:123], v[136:139], v[176:179], v[120:123]
	v_mfma_f32_16x16x32_bf16 v[108:111], v[128:131], v[184:187], v[108:111]
	v_mfma_f32_16x16x32_bf16 v[104:107], v[136:139], v[184:187], v[104:107]
	v_mfma_f32_16x16x32_bf16 v[92:95], v[128:131], v[200:203], v[92:95]
	v_mfma_f32_16x16x32_bf16 v[88:91], v[136:139], v[200:203], v[88:91]
	v_mfma_f32_16x16x32_bf16 v[76:79], v[128:131], v[208:211], v[76:79]
	v_mfma_f32_16x16x32_bf16 v[72:75], v[136:139], v[208:211], v[72:75]
	v_mfma_f32_16x16x32_bf16 v[124:127], v[132:135], v[180:183], v[124:127]
	v_mfma_f32_16x16x32_bf16 v[120:123], v[140:143], v[180:183], v[120:123]
	v_mfma_f32_16x16x32_bf16 v[108:111], v[132:135], v[188:191], v[108:111]
	v_mfma_f32_16x16x32_bf16 v[104:107], v[140:143], v[188:191], v[104:107]
	v_mfma_f32_16x16x32_bf16 v[92:95], v[132:135], v[204:207], v[92:95]
	v_mfma_f32_16x16x32_bf16 v[88:91], v[140:143], v[204:207], v[88:91]
	v_mfma_f32_16x16x32_bf16 v[76:79], v[132:135], v[212:215], v[76:79]
	v_mfma_f32_16x16x32_bf16 v[72:75], v[140:143], v[212:215], v[72:75]
	s_setprio 0
	s_setprio 1
	v_mfma_f32_16x16x32_bf16 v[116:119], v[156:159], v[176:179], v[116:119]
	v_mfma_f32_16x16x32_bf16 v[112:115], v[168:171], v[176:179], v[112:115]
	v_mfma_f32_16x16x32_bf16 v[100:103], v[156:159], v[184:187], v[100:103]
	v_mfma_f32_16x16x32_bf16 v[96:99], v[168:171], v[184:187], v[96:99]
	v_mfma_f32_16x16x32_bf16 v[84:87], v[156:159], v[200:203], v[84:87]
	v_mfma_f32_16x16x32_bf16 v[80:83], v[168:171], v[200:203], v[80:83]
	v_mfma_f32_16x16x32_bf16 v[68:71], v[156:159], v[208:211], v[68:71]
	v_mfma_f32_16x16x32_bf16 v[64:67], v[168:171], v[208:211], v[64:67]
	v_mfma_f32_16x16x32_bf16 v[116:119], v[160:163], v[180:183], v[116:119]
	v_mfma_f32_16x16x32_bf16 v[112:115], v[172:175], v[180:183], v[112:115]
	v_mfma_f32_16x16x32_bf16 v[100:103], v[160:163], v[188:191], v[100:103]
	v_mfma_f32_16x16x32_bf16 v[96:99], v[172:175], v[188:191], v[96:99]
	v_mfma_f32_16x16x32_bf16 v[84:87], v[160:163], v[204:207], v[84:87]
	v_mfma_f32_16x16x32_bf16 v[80:83], v[172:175], v[204:207], v[80:83]
	v_mfma_f32_16x16x32_bf16 v[68:71], v[160:163], v[212:215], v[68:71]
	v_mfma_f32_16x16x32_bf16 v[64:67], v[172:175], v[212:215], v[64:67]
	s_setprio 0
	s_barrier
	s_add_i32 s47, s47, s30
	v_lshl_add_u64 v[192:193], s[22:23], 0, v[148:149]
	s_mov_b32 m0, s47
	ds_read_b128 v[176:179], v166 offset:16384
	ds_read_b128 v[180:183], v166 offset:17408
	ds_read_b128 v[184:187], v166 offset:18432
	ds_read_b128 v[188:191], v166 offset:19456
	ds_read_b128 v[200:203], v166 offset:20480
	ds_read_b128 v[204:207], v166 offset:21504
	ds_read_b128 v[208:211], v166 offset:22528
	ds_read_b128 v[212:215], v166 offset:23552
	global_load_lds_dwordx4 v[192:193], off
	s_add_i32 m0, s47, 0x2000
	s_add_u32 s48, s22, 0x20000
	v_lshl_add_u64 v[196:197], s[22:23], 0, v[144:145]
	s_addc_u32 s49, s23, 0
	s_add_i32 s47, s50, s30
	global_load_lds_dwordx4 v[196:197], off
	v_lshl_add_u64 v[198:199], s[48:49], 0, v[148:149]
	s_mov_b32 m0, s47
	v_lshl_add_u64 v[216:217], s[24:25], 0, v[146:147]
	global_load_lds_dwordx4 v[198:199], off
	v_lshl_add_u64 v[198:199], s[48:49], 0, v[144:145]
	s_add_i32 m0, s47, 0x2000
	s_nop 0
	global_load_lds_dwordx4 v[198:199], off
	v_lshl_add_u64 v[198:199], s[24:25], 0, v[150:151]
	s_mov_b32 m0, s31
	s_nop 0
	global_load_lds_dwordx4 v[198:199], off
	s_mov_b32 m0, s34
	s_nop 0
	global_load_lds_dwordx4 v[216:217], off
	s_waitcnt vmcnt(8)
	s_waitcnt lgkmcnt(0)
	s_barrier
; #define PG8_STAGE(bufoff, gbase, voff) do { _Pragma("unroll") for (int _i = 0; _i < 2; ++_i) \
;         __builtin_amdgcn_global_load_lds((const unsigned*)((const char*)(gbase) + (voff)[_i]), (LAS unsigned*)(lds + (bufoff) + ldsw + _i * 8192), 16, 0, 0); } while (0)
; #define PG8_LDA(dst, b, h) do { _Pragma("unroll") for (int m = 0; m < 4; ++m) _Pragma("unroll") for (int k = 0; k < 2; ++k) dst[m][k] = *(const LAS bf16x8*)(lds + PG8_SA(b, h) + aoff + m * 2048 + k * 1024); } while (0)
; #define PG8_LDB(dst, b, h) do { _Pragma("unroll") for (int n = 0; n < 2; ++n) _Pragma("unroll") for (int k = 0; k < 2; ++k) dst[n][k] = *(const LAS bf16x8*)(lds + PG8_SB(b, h) + boff + n * 2048 + k * 1024); } while (0)
; #define PG8_MMA(ai, bj, At, Bt) do { __builtin_amdgcn_s_setprio(1); _Pragma("unroll") for (int m = 0; m < 4; ++m) _Pragma("unroll") for (int n = 0; n < 2; ++n) _Pragma("unroll") for (int k = 0; k < 2; ++k) \
;         acc[ai][bj][m][n] = __builtin_amdgcn_mfma_f32_16x16x32_bf16(Bt[n][k], At[m][k], acc[ai][bj][m][n], 0, 0, 0); __builtin_amdgcn_s_setprio(0); } while (0)
; #define PG8_WAIT_V(n) asm volatile("s_waitcnt vmcnt(" #n ")" ::: "memory")
; #define PG8_WAIT_L(n) asm volatile("s_waitcnt lgkmcnt(" #n ")" ::: "memory")
; #define PG8_BAR __builtin_amdgcn_s_barrier()
; #define PG8_SCHED __builtin_amdgcn_sched_barrier(0)
; template <class Epi, class Sched>
; __device__ __forceinline__ void gemm_stream(LAS unsigned char* lds, const int lda, const int ldb, const Sched& S, const Epi& E, const int wv) {
;     ...
;             PG8_WAIT_V(8); PG8_WAIT_L(0); PG8_BAR; PG8_MMA(1, 0, At, B0); PG8_MMA(1, 1, At, B1); PG8_BAR; PG8_SCHED;
;             PG8_LDB(B0, 1, 0); PG8_LDB(B1, 1, 1); PG8_SCHED; PG8_LDA(At, 1, 0); PG8_STAGE(PG8_SA(0, 1), a2 + hstepA, voffA);
;             PG8_WAIT_V(8); PG8_WAIT_L(0); PG8_BAR; PG8_MMA(0, 0, At, B0); PG8_MMA(0, 1, At, B1); PG8_BAR; PG8_SCHED;
	s_setprio 1
	v_mfma_f32_16x16x32_bf16 v[60:63], v[128:131], v[176:179], v[60:63]
	v_mfma_f32_16x16x32_bf16 v[56:59], v[136:139], v[176:179], v[56:59]
	v_mfma_f32_16x16x32_bf16 v[44:47], v[128:131], v[184:187], v[44:47]
	v_mfma_f32_16x16x32_bf16 v[40:43], v[136:139], v[184:187], v[40:43]
	v_mfma_f32_16x16x32_bf16 v[28:31], v[128:131], v[200:203], v[28:31]
	v_mfma_f32_16x16x32_bf16 v[24:27], v[136:139], v[200:203], v[24:27]
	v_mfma_f32_16x16x32_bf16 v[12:15], v[128:131], v[208:211], v[12:15]
	v_mfma_f32_16x16x32_bf16 v[8:11], v[136:139], v[208:211], v[8:11]
	v_mfma_f32_16x16x32_bf16 v[60:63], v[132:135], v[180:183], v[60:63]
	v_mfma_f32_16x16x32_bf16 v[56:59], v[140:143], v[180:183], v[56:59]
	v_mfma_f32_16x16x32_bf16 v[44:47], v[132:135], v[188:191], v[44:47]
	v_mfma_f32_16x16x32_bf16 v[40:43], v[140:143], v[188:191], v[40:43]
	v_mfma_f32_16x16x32_bf16 v[28:31], v[132:135], v[204:207], v[28:31]
	v_mfma_f32_16x16x32_bf16 v[24:27], v[140:143], v[204:207], v[24:27]
	v_mfma_f32_16x16x32_bf16 v[12:15], v[132:135], v[212:215], v[12:15]
	v_mfma_f32_16x16x32_bf16 v[8:11], v[140:143], v[212:215], v[8:11]
	s_setprio 0
	s_setprio 1
	v_mfma_f32_16x16x32_bf16 v[52:55], v[156:159], v[176:179], v[52:55]
	v_mfma_f32_16x16x32_bf16 v[48:51], v[168:171], v[176:179], v[48:51]
	v_mfma_f32_16x16x32_bf16 v[36:39], v[156:159], v[184:187], v[36:39]
	v_mfma_f32_16x16x32_bf16 v[32:35], v[168:171], v[184:187], v[32:35]
	v_mfma_f32_16x16x32_bf16 v[20:23], v[156:159], v[200:203], v[20:23]
	v_mfma_f32_16x16x32_bf16 v[16:19], v[168:171], v[200:203], v[16:19]
	v_mfma_f32_16x16x32_bf16 v[4:7], v[156:159], v[208:211], v[4:7]
	v_mfma_f32_16x16x32_bf16 v[0:3], v[168:171], v[208:211], v[0:3]
	v_mfma_f32_16x16x32_bf16 v[52:55], v[160:163], v[180:183], v[52:55]
	v_mfma_f32_16x16x32_bf16 v[48:51], v[172:175], v[180:183], v[48:51]
	v_mfma_f32_16x16x32_bf16 v[36:39], v[160:163], v[188:191], v[36:39]
	v_mfma_f32_16x16x32_bf16 v[32:35], v[172:175], v[188:191], v[32:35]
	v_mfma_f32_16x16x32_bf16 v[20:23], v[160:163], v[204:207], v[20:23]
	v_mfma_f32_16x16x32_bf16 v[16:19], v[172:175], v[204:207], v[16:19]
	v_mfma_f32_16x16x32_bf16 v[4:7], v[160:163], v[212:215], v[4:7]
	v_mfma_f32_16x16x32_bf16 v[0:3], v[172:175], v[212:215], v[0:3]
	s_setprio 0
	s_barrier
	s_add_i32 s47, 0, 0x18000
	s_add_i32 s48, 0, 0x1c000
	v_add_u32_e32 v140, s47, v165
	v_add_u32_e32 v167, s48, v165
	ds_read_b128 v[128:131], v140
	ds_read_b128 v[132:135], v140 offset:1024
	ds_read_b128 v[136:139], v140 offset:2048
	ds_read_b128 v[140:143], v140 offset:3072
	ds_read_b128 v[156:159], v167
	ds_read_b128 v[160:163], v167 offset:1024
	ds_read_b128 v[168:171], v167 offset:2048
	ds_read_b128 v[172:175], v167 offset:3072
	s_add_u32 s24, s24, 0x80000
	s_addc_u32 s25, s25, 0
	s_mov_b32 m0, s35
	v_lshl_add_u64 v[218:219], s[24:25], 0, v[150:151]
	ds_read_b128 v[176:179], v166 offset:32768
	ds_read_b128 v[180:183], v166 offset:33792
	ds_read_b128 v[184:187], v166 offset:34816
	ds_read_b128 v[188:191], v166 offset:35840
	ds_read_b128 v[200:203], v166 offset:36864
	ds_read_b128 v[204:207], v166 offset:37888
	ds_read_b128 v[208:211], v166 offset:38912
	ds_read_b128 v[212:215], v166 offset:39936
	global_load_lds_dwordx4 v[218:219], off
	v_lshl_add_u64 v[218:219], s[24:25], 0, v[146:147]
	s_mov_b32 m0, s36
	s_nop 0
	global_load_lds_dwordx4 v[218:219], off
	s_waitcnt vmcnt(8)
	s_waitcnt lgkmcnt(0)
	s_barrier
	s_setprio 1
	v_mfma_f32_16x16x32_bf16 v[124:127], v[128:131], v[176:179], v[124:127]
	v_mfma_f32_16x16x32_bf16 v[120:123], v[136:139], v[176:179], v[120:123]
	v_mfma_f32_16x16x32_bf16 v[108:111], v[128:131], v[184:187], v[108:111]
	v_mfma_f32_16x16x32_bf16 v[104:107], v[136:139], v[184:187], v[104:107]
	v_mfma_f32_16x16x32_bf16 v[92:95], v[128:131], v[200:203], v[92:95]
	v_mfma_f32_16x16x32_bf16 v[88:91], v[136:139], v[200:203], v[88:91]
	v_mfma_f32_16x16x32_bf16 v[76:79], v[128:131], v[208:211], v[76:79]
	v_mfma_f32_16x16x32_bf16 v[72:75], v[136:139], v[208:211], v[72:75]
	v_mfma_f32_16x16x32_bf16 v[124:127], v[132:135], v[180:183], v[124:127]
	v_mfma_f32_16x16x32_bf16 v[120:123], v[140:143], v[180:183], v[120:123]
	v_mfma_f32_16x16x32_bf16 v[108:111], v[132:135], v[188:191], v[108:111]
	v_mfma_f32_16x16x32_bf16 v[104:107], v[140:143], v[188:191], v[104:107]
	v_mfma_f32_16x16x32_bf16 v[92:95], v[132:135], v[204:207], v[92:95]
	v_mfma_f32_16x16x32_bf16 v[88:91], v[140:143], v[204:207], v[88:91]
	v_mfma_f32_16x16x32_bf16 v[76:79], v[132:135], v[212:215], v[76:79]
	v_mfma_f32_16x16x32_bf16 v[72:75], v[140:143], v[212:215], v[72:75]
	s_setprio 0
	s_setprio 1
	v_mfma_f32_16x16x32_bf16 v[116:119], v[156:159], v[176:179], v[116:119]
	v_mfma_f32_16x16x32_bf16 v[112:115], v[168:171], v[176:179], v[112:115]
	v_mfma_f32_16x16x32_bf16 v[100:103], v[156:159], v[184:187], v[100:103]
	v_mfma_f32_16x16x32_bf16 v[96:99], v[168:171], v[184:187], v[96:99]
	v_mfma_f32_16x16x32_bf16 v[84:87], v[156:159], v[200:203], v[84:87]
	v_mfma_f32_16x16x32_bf16 v[80:83], v[168:171], v[200:203], v[80:83]
	v_mfma_f32_16x16x32_bf16 v[68:71], v[156:159], v[208:211], v[68:71]
	v_mfma_f32_16x16x32_bf16 v[64:67], v[168:171], v[208:211], v[64:67]
	v_mfma_f32_16x16x32_bf16 v[116:119], v[160:163], v[180:183], v[116:119]
	v_mfma_f32_16x16x32_bf16 v[112:115], v[172:175], v[180:183], v[112:115]
	v_mfma_f32_16x16x32_bf16 v[100:103], v[160:163], v[188:191], v[100:103]
	v_mfma_f32_16x16x32_bf16 v[96:99], v[172:175], v[188:191], v[96:99]
	v_mfma_f32_16x16x32_bf16 v[84:87], v[160:163], v[204:207], v[84:87]
	v_mfma_f32_16x16x32_bf16 v[80:83], v[172:175], v[204:207], v[80:83]
	v_mfma_f32_16x16x32_bf16 v[68:71], v[160:163], v[212:215], v[68:71]
	v_mfma_f32_16x16x32_bf16 v[64:67], v[172:175], v[212:215], v[64:67]
	s_setprio 0
	s_barrier
; #define PG8_STAGE(bufoff, gbase, voff) do { _Pragma("unroll") for (int _i = 0; _i < 2; ++_i) \
;         __builtin_amdgcn_global_load_lds((const unsigned*)((const char*)(gbase) + (voff)[_i]), (LAS unsigned*)(lds + (bufoff) + ldsw + _i * 8192), 16, 0, 0); } while (0)
; #define PG8_LDA(dst, b, h) do { _Pragma("unroll") for (int m = 0; m < 4; ++m) _Pragma("unroll") for (int k = 0; k < 2; ++k) dst[m][k] = *(const LAS bf16x8*)(lds + PG8_SA(b, h) + aoff + m * 2048 + k * 1024); } while (0)
; #define PG8_MMA(ai, bj, At, Bt) do { __builtin_amdgcn_s_setprio(1); _Pragma("unroll") for (int m = 0; m < 4; ++m) _Pragma("unroll") for (int n = 0; n < 2; ++n) _Pragma("unroll") for (int k = 0; k < 2; ++k) \
;         acc[ai][bj][m][n] = __builtin_amdgcn_mfma_f32_16x16x32_bf16(Bt[n][k], At[m][k], acc[ai][bj][m][n], 0, 0, 0); __builtin_amdgcn_s_setprio(0); } while (0)
; #define PG8_WAIT_V(n) asm volatile("s_waitcnt vmcnt(" #n ")" ::: "memory")
; #define PG8_WAIT_L(n) asm volatile("s_waitcnt lgkmcnt(" #n ")" ::: "memory")
; #define PG8_BAR __builtin_amdgcn_s_barrier()
; #define PG8_SCHED __builtin_amdgcn_sched_barrier(0)
; template <class Epi, class Sched>
; __device__ __forceinline__ void gemm_stream(LAS unsigned char* lds, const int lda, const int ldb, const Sched& S, const Epi& E, const int wv) {
;     ...
;             PG8_LDA(At, 1, 1); PG8_STAGE(PG8_SB(1, 0), b3, voffB); PG8_STAGE(PG8_SB(1, 1), b3 + hstepB, voffB); PG8_STAGE(PG8_SA(1, 0), a3, voffA);
;             PG8_WAIT_V(8); PG8_WAIT_L(0); PG8_BAR; PG8_MMA(1, 0, At, B0); PG8_MMA(1, 1, At, B1); PG8_BAR; PG8_SCHED;
;         }
;         if (wr == 0) PG8_BAR;
	s_add_i32 s24, s47, s30
	v_lshl_add_u64 v[192:193], v[192:193], 0, s[78:79]
	s_mov_b32 m0, s24
	ds_read_b128 v[176:179], v166 offset:49152
	ds_read_b128 v[180:183], v166 offset:50176
	ds_read_b128 v[184:187], v166 offset:51200
	ds_read_b128 v[188:191], v166 offset:52224
	ds_read_b128 v[200:203], v166 offset:53248
	ds_read_b128 v[204:207], v166 offset:54272
	ds_read_b128 v[208:211], v166 offset:55296
	ds_read_b128 v[212:215], v166 offset:56320
	global_load_lds_dwordx4 v[192:193], off
	s_add_i32 m0, s24, 0x2000
	s_add_u32 s22, s22, 0x20080
	v_lshl_add_u64 v[192:193], v[196:197], 0, s[78:79]
	s_addc_u32 s23, s23, 0
	s_add_i32 s24, s48, s30
	global_load_lds_dwordx4 v[192:193], off
	v_lshl_add_u64 v[192:193], s[22:23], 0, v[148:149]
	s_mov_b32 m0, s24
	s_nop 0
	global_load_lds_dwordx4 v[192:193], off
	v_lshl_add_u64 v[192:193], s[22:23], 0, v[144:145]
	s_add_i32 m0, s24, 0x2000
	s_nop 0
	global_load_lds_dwordx4 v[192:193], off
	v_lshl_add_u64 v[192:193], v[198:199], 0, s[78:79]
	s_mov_b32 m0, s40
	s_nop 0
	global_load_lds_dwordx4 v[192:193], off
	v_lshl_add_u64 v[192:193], v[216:217], 0, s[78:79]
	s_mov_b32 m0, s41
	s_nop 0
	global_load_lds_dwordx4 v[192:193], off
	s_waitcnt vmcnt(8)
	s_waitcnt lgkmcnt(0)
	s_barrier
	s_setprio 1
	v_mfma_f32_16x16x32_bf16 v[60:63], v[128:131], v[176:179], v[60:63]
	v_mfma_f32_16x16x32_bf16 v[56:59], v[136:139], v[176:179], v[56:59]
	v_mfma_f32_16x16x32_bf16 v[44:47], v[128:131], v[184:187], v[44:47]
	v_mfma_f32_16x16x32_bf16 v[40:43], v[136:139], v[184:187], v[40:43]
	v_mfma_f32_16x16x32_bf16 v[28:31], v[128:131], v[200:203], v[28:31]
	v_mfma_f32_16x16x32_bf16 v[24:27], v[136:139], v[200:203], v[24:27]
	v_mfma_f32_16x16x32_bf16 v[12:15], v[128:131], v[208:211], v[12:15]
	v_mfma_f32_16x16x32_bf16 v[8:11], v[136:139], v[208:211], v[8:11]
	v_mfma_f32_16x16x32_bf16 v[60:63], v[132:135], v[180:183], v[60:63]
	v_mfma_f32_16x16x32_bf16 v[56:59], v[140:143], v[180:183], v[56:59]
	v_mfma_f32_16x16x32_bf16 v[44:47], v[132:135], v[188:191], v[44:47]
	v_mfma_f32_16x16x32_bf16 v[40:43], v[140:143], v[188:191], v[40:43]
	v_mfma_f32_16x16x32_bf16 v[28:31], v[132:135], v[204:207], v[28:31]
	v_mfma_f32_16x16x32_bf16 v[24:27], v[140:143], v[204:207], v[24:27]
	v_mfma_f32_16x16x32_bf16 v[12:15], v[132:135], v[212:215], v[12:15]
	v_mfma_f32_16x16x32_bf16 v[8:11], v[140:143], v[212:215], v[8:11]
	s_setprio 0
	s_setprio 1
	v_mfma_f32_16x16x32_bf16 v[52:55], v[156:159], v[176:179], v[52:55]
	v_mfma_f32_16x16x32_bf16 v[48:51], v[168:171], v[176:179], v[48:51]
	v_mfma_f32_16x16x32_bf16 v[36:39], v[156:159], v[184:187], v[36:39]
	v_mfma_f32_16x16x32_bf16 v[32:35], v[168:171], v[184:187], v[32:35]
	v_mfma_f32_16x16x32_bf16 v[20:23], v[156:159], v[200:203], v[20:23]
	v_mfma_f32_16x16x32_bf16 v[16:19], v[168:171], v[200:203], v[16:19]
	v_mfma_f32_16x16x32_bf16 v[4:7], v[156:159], v[208:211], v[4:7]
	v_mfma_f32_16x16x32_bf16 v[0:3], v[168:171], v[208:211], v[0:3]
	v_mfma_f32_16x16x32_bf16 v[52:55], v[160:163], v[180:183], v[52:55]
	v_mfma_f32_16x16x32_bf16 v[48:51], v[172:175], v[180:183], v[48:51]
	v_mfma_f32_16x16x32_bf16 v[36:39], v[160:163], v[188:191], v[36:39]
	v_mfma_f32_16x16x32_bf16 v[32:35], v[172:175], v[188:191], v[32:35]
	v_mfma_f32_16x16x32_bf16 v[20:23], v[160:163], v[204:207], v[20:23]
	v_mfma_f32_16x16x32_bf16 v[16:19], v[172:175], v[204:207], v[16:19]
	v_mfma_f32_16x16x32_bf16 v[4:7], v[160:163], v[212:215], v[4:7]
	v_mfma_f32_16x16x32_bf16 v[0:3], v[172:175], v[212:215], v[0:3]
	s_setprio 0
	s_barrier
	s_add_i32 s46, s46, 2
	s_add_u32 s20, s20, 0x100
	s_addc_u32 s21, s21, 0
	s_add_u32 s13, s13, 0x100
	s_addc_u32 s15, s15, 0
	s_cmp_gt_u32 s46, 29
	s_cbranch_scc0 .LBB0_600
	s_and_b64 vcc, exec, s[6:7]
	s_cbranch_vccz .LBB0_603
	s_barrier
